# vtr: attention V tile row-major in LDS (2 ds_write_b128/thread, coalesced thread map) read via ds_read_b64_tr_b16; replaces vmap
# speedup vs baseline: 1.0061x; 1.0061x over previous
; __device__ __forceinline__ void attn_phase(const Params& p, char* smem) {
;   const int tid = otid(), lane = tid & 63, w = tid >> 6, fr = lane & 15, fq = lane >> 4;
;   bf16_t* Ks = (bf16_t*)smem;
;   bf16_t* Vt = Ks + 2 * KT * KLD;
;   const bf16_t* Qg = p.ACT();
;   const bf16_t* Kg = p.ACT() + (size_t)16 * TPB * 96;
;   const bf16_t* KVRAW = p.R() + (size_t)NTOK * 768;
;   bf16_t* MIX = p.H();
;   for (int it = obid(); it < 272; it += gridDim.x) {
;     int bh, qu0, nq, nkeys;
;     if (it < 256) { int xx = it & 7, k = it >> 3; bh = 2 * xx + (k >> 4); qu0 = CTX + (k & 15) * 512; nq = 512; nkeys = TPB; }
;     else { bh = it - 256; qu0 = 0; nq = 256; nkeys = CTX; }
;     const int b = bh >> 3, h = bh & 7;
;     const bool active = (w * 64) < nq;
;     bf16x8 qf[4][3];
;     if (active) {
; #pragma unroll
;       for (int g = 0; g < 4; ++g) {
;         const bf16_t* qp = Qg + ((size_t)bh * TPB + qu0 + w * 64 + g * 16 + fr) * 96 + fq * 8;
; #pragma unroll
;         for (int ds = 0; ds < 3; ++ds) qf[g][ds] = *(const bf16x8*)(qp + ds * 32);
;       }
;     }
;     f32x4 oT[4][4];
;     float mneg[4], lrun[4];
;     float bmax = 0.f;
;     {
;       const float kmx = sqrtf(__uint_as_float(p.kmax2()[bh]) + __uint_as_float(p.kmax2()[16 + bh])) * 1.01f;
; #pragma unroll
;       for (int g = 0; g < 4; ++g) {
;         float qs = 0.f;
;         if (active) {
; #pragma unroll
;           for (int ds = 0; ds < 3; ++ds)
; #pragma unroll
;             for (int e = 0; e < 8; ++e) { float qv = bf2f((bf16_t)qf[g][ds][e]); qs += qv * qv; }
;         }
;         qs += __shfl_xor(qs, 16); qs += __shfl_xor(qs, 32);
;         mneg[g] = -sqrtf(qs) * kmx;
;         bmax = fmaxf(bmax, -mneg[g]);
;         lrun[g] = 0.f;
; #pragma unroll
;         for (int q = 0; q < 4; ++q) oT[g][q] = (f32x4){0.f, 0.f, 0.f, 0.f};
;       }
;     }
;     const bool stab = __any(bmax > 60.0f) != 0;
;     const bf16_t* kbase = Kg + (size_t)bh * TPB * 96;
;     const bf16_t* vbase = KVRAW + (size_t)b * TPB * 1024 + h * 128 + 64;
;     ...
;     uint4 rk0, rk1, rk2, rv0, rv1;
;     const int nkt = nkeys / KT;
;     rk0 = *(const uint4*)(kbase + kgo); rk1 = *(const uint4*)(kbase + kgo + 8); rk2 = *(const uint4*)(kbase + kgo + 16);
;     rv0 = *(const uint4*)(vbase + (size_t)vkey0 * 1024 + vch * 8); rv1 = *(const uint4*)(vbase + (size_t)(vkey0 + 64) * 1024 + vch * 8);
.LBB0_392:
	s_and_b64 vcc, exec, s[2:3]
	s_cbranch_vccz .LBB0_426
	v_mov_b32_e32 v0, v164
	s_mov_b32 s12, s82
	s_cmpk_gt_i32 s12, 0x10f
	s_cbranch_scc1 .LBB0_426
	s_load_dwordx2 s[44:45], s[0:1], 0xf0
	v_bfe_u32 v1, v0, 4, 2
	v_lshlrev_b32_e32 v2, 4, v1
	v_mov_b32_e32 v3, v167
	v_lshlrev_b32_e32 v166, 3, v1
	s_waitcnt lgkmcnt(0)
	v_lshl_add_u64 v[4:5], s[44:45], 0, v[2:3]
	v_and_b32_e32 v3, 64, v231
	v_xor_b32_e32 v1, 16, v231
	v_add_u32_e32 v3, 64, v3
	v_cmp_lt_i32_e32 vcc, v1, v3
	s_mov_b64 s[2:3], 0x7290000
	v_lshl_add_u64 v[180:181], v[4:5], 0, s[2:3]
	v_cndmask_b32_e32 v1, v231, v1, vcc
	v_lshlrev_b32_e32 v235, 2, v1
	v_xor_b32_e32 v1, 32, v231
	v_cmp_lt_i32_e32 vcc, v1, v3
	s_movk_i32 s2, 0x60
	v_and_b32_e32 v4, 3, v0
	v_cndmask_b32_e32 v1, v231, v1, vcc
	v_lshlrev_b32_e32 v236, 2, v1
	v_ashrrev_i32_e32 v1, 2, v0
	v_mul_lo_u32 v3, v1, s2
	v_mul_u32_u24_e32 v10, 24, v4
	v_mad_u32_u24 v4, v4, 24, v3
	v_ashrrev_i32_e32 v6, 3, v0
	v_lshlrev_b32_e32 v3, 3, v0
	s_movk_i32 s4, 0xd0
	v_ashrrev_i32_e32 v7, 31, v6
	v_and_b32_e32 v8, 56, v3
	v_mul_lo_u32 v1, v1, s4
	v_lshlrev_b32_e32 v3, 1, v10
	v_lshlrev_b64 v[182:183], 11, v[6:7]
	s_mov_b64 s[2:3], 0x20000
	v_add3_u32 v237, 0, v1, v3
	v_mul_u32_u24_e32 v1, 0xa0, v6
	v_lshlrev_b32_e32 v3, 1, v8
	v_and_b32_e32 v9, 15, v0
	v_and_b32_e32 v171, 0xffffffc0, v0
	v_ashrrev_i32_e32 v5, 31, v4
	v_lshl_add_u64 v[184:185], v[182:183], 0, s[2:3]
	v_add3_u32 v238, 0, v1, v3
	v_and_b32_e32 v239, 0xffffffcf, v0
	v_bfe_u32 v10, v0, 4, 2
	v_bfe_u32 v11, v0, 2, 2
	v_lshl_add_u32 v10, v10, 2, v11
	v_and_b32_e32 v11, 3, v0
	v_mul_u32_u24_e32 v10, 0xa0, v10
	v_lshl_add_u32 v240, v11, 3, v10
	v_lshl_add_u64 v[0:1], s[44:45], 0, v[166:167]
	s_mov_b64 s[2:3], 0x5190000
	v_lshl_add_u64 v[186:187], v[0:1], 0, s[2:3]
	v_lshl_add_u64 v[0:1], v[4:5], 1, s[44:45]
	s_mov_b64 s[2:3], 0x8b50000
	v_lshl_add_u64 v[188:189], v[0:1], 0, s[2:3]
	s_add_u32 s13, s44, 0x115d0900
	s_movk_i32 s2, 0x110
	v_ashrrev_i32_e32 v179, 31, v171
	v_or_b32_e32 v178, v171, v9
	s_addc_u32 s14, s45, 0
	v_mad_u32_u24 v241, v9, s4, v2
	v_lshlrev_b32_e32 v166, 1, v8
	s_branch .LBB0_396

;   __host__ __device__ __forceinline__ unsigned* kmax2() const { return (unsigned*)(wsl() + OFF_KMAX); }
; __device__ __forceinline__ float bf2f(bf16_t h) { return __uint_as_float(((uint32_t)h) << 16); }
; __device__ __forceinline__ void attn_phase(const Params& p, char* smem) {
;     ...
;     float mneg[4], lrun[4];
;     float bmax = 0.f;
;     {
;       const float kmx = sqrtf(__uint_as_float(p.kmax2()[bh]) + __uint_as_float(p.kmax2()[16 + bh])) * 1.01f;
; #pragma unroll
;       for (int g = 0; g < 4; ++g) {
;         float qs = 0.f;
;         if (active) {
; #pragma unroll
;           for (int ds = 0; ds < 3; ++ds)
; #pragma unroll
;             for (int e = 0; e < 8; ++e) { float qv = bf2f((bf16_t)qf[g][ds][e]); qs += qv * qv; }
;         }
;         qs += __shfl_xor(qs, 16); qs += __shfl_xor(qs, 32);
;         mneg[g] = -sqrtf(qs) * kmx;
;         bmax = fmaxf(bmax, -mneg[g]);
;         lrun[g] = 0.f;
; #pragma unroll
;         for (int q = 0; q < 4; ++q) oT[g][q] = (f32x4){0.f, 0.f, 0.f, 0.f};
;       }
;     }
;     const bool stab = __any(bmax > 60.0f) != 0;
;     const bf16_t* kbase = Kg + (size_t)bh * TPB * 96;
;     const bf16_t* vbase = KVRAW + (size_t)b * TPB * 1024 + h * 128 + 64;
;     ...
;     uint4 rk0, rk1, rk2, rv0, rv1;
;     const int nkt = nkeys / KT;
;     rk0 = *(const uint4*)(kbase + kgo); rk1 = *(const uint4*)(kbase + kgo + 8); rk2 = *(const uint4*)(kbase + kgo + 16);
;     rv0 = *(const uint4*)(vbase + (size_t)vkey0 * 1024 + vch * 8); rv1 = *(const uint4*)(vbase + (size_t)(vkey0 + 64) * 1024 + vch * 8);
;     {
;       *(uint4*)(Ks + klo) = rk0; *(uint4*)(Ks + klo + 8) = rk1; *(uint4*)(Ks + klo + 16) = rk2;
;       vt_scatter(Vt + (vch * 8) * VLD + vkey0, VLD, rv0); vt_scatter(Vt + (vch * 8) * VLD + vkey0 + 64, VLD, rv1);
;     }
;     __syncthreads();
.LBB0_410:
	s_or_b64 exec, exec, s[4:5]
	s_waitcnt vmcnt(0)
	v_add_f32_e32 v48, v48, v49
	s_mov_b32 s3, 0xf800000
	v_mul_f32_e32 v49, 0x4f800000, v48
	v_cmp_gt_f32_e32 vcc, s3, v48
	v_add_f32_e32 v50, v50, v51
	v_mul_f32_e32 v51, 0x4f800000, v50
	v_cndmask_b32_e32 v48, v48, v49, vcc
	v_sqrt_f32_e32 v49, v48
	s_mov_b32 s4, 0x42700000
	s_ashr_i32 s15, s6, 3
	s_mul_i32 s8, s15, 0x1080000
	v_add_u32_e32 v57, -1, v49
	v_fma_f32 v59, -v57, v49, v48
	v_add_u32_e32 v58, 1, v49
	v_cmp_ge_f32_e64 s[42:43], 0, v59
	s_mul_hi_i32 s7, s15, 0x1080000
	v_mov_b32_e32 v80, v167
	v_cndmask_b32_e64 v57, v49, v57, s[42:43]
	v_fma_f32 v49, -v58, v49, v48
	v_cmp_lt_f32_e64 s[42:43], 0, v49
	v_mov_b32_e32 v81, v167
	v_mov_b32_e32 v82, v167
	v_cndmask_b32_e64 v49, v57, v58, s[42:43]
	v_mul_f32_e32 v57, 0x37800000, v49
	v_cndmask_b32_e32 v49, v49, v57, vcc
	v_cmp_gt_f32_e32 vcc, s3, v50
	v_cmp_class_f32_e64 s[42:43], v48, v216
	v_mov_b32_e32 v83, v167
	v_cndmask_b32_e32 v50, v50, v51, vcc
	v_sqrt_f32_e32 v51, v50
	v_cndmask_b32_e64 v48, v49, v48, s[42:43]
	v_mul_f32_e32 v48, 0x3f8147ae, v48
	v_mov_b32_e32 v190, v167
	v_add_u32_e32 v49, -1, v51
	v_fma_f32 v57, -v49, v51, v50
	v_cmp_ge_f32_e64 s[42:43], 0, v57
	v_add_u32_e32 v57, 1, v51
	v_mov_b32_e32 v191, v167
	v_cndmask_b32_e64 v49, v51, v49, s[42:43]
	v_fma_f32 v51, -v57, v51, v50
	v_cmp_lt_f32_e64 s[42:43], 0, v51
	v_mov_b64_e32 v[86:87], v[82:83]
	v_mov_b64_e32 v[90:91], v[82:83]
	v_cndmask_b32_e64 v49, v49, v57, s[42:43]
	v_mul_f32_e32 v51, 0x37800000, v49
	v_cndmask_b32_e32 v49, v49, v51, vcc
	v_add_f32_e32 v51, v52, v53
	v_mul_f32_e32 v52, 0x4f800000, v51
	v_cmp_gt_f32_e32 vcc, s3, v51
	v_cmp_class_f32_e64 s[42:43], v50, v216
	v_mov_b64_e32 v[94:95], v[82:83]
	v_cndmask_b32_e32 v51, v51, v52, vcc
	v_sqrt_f32_e32 v52, v51
	v_cndmask_b32_e64 v49, v49, v50, s[42:43]
	v_mul_f32_e64 v192, v48, -v49
	v_mov_b64_e32 v[98:99], v[82:83]
	v_add_u32_e32 v49, -1, v52
	v_fma_f32 v50, -v49, v52, v51
	v_cmp_ge_f32_e64 s[42:43], 0, v50
	v_add_u32_e32 v50, 1, v52
	v_mov_b64_e32 v[102:103], v[82:83]
	v_cndmask_b32_e64 v49, v52, v49, s[42:43]
	v_fma_f32 v52, -v50, v52, v51
	v_cmp_lt_f32_e64 s[42:43], 0, v52
	v_mov_b64_e32 v[106:107], v[82:83]
	v_mov_b64_e32 v[110:111], v[82:83]
	v_cndmask_b32_e64 v49, v49, v50, s[42:43]
	v_mul_f32_e32 v50, 0x37800000, v49
	v_cndmask_b32_e32 v49, v49, v50, vcc
	s_waitcnt lgkmcnt(0)
	v_add_f32_e32 v50, v55, v56
	v_mul_f32_e32 v52, 0x4f800000, v50
	v_cmp_gt_f32_e32 vcc, s3, v50
	v_cmp_class_f32_e64 s[42:43], v51, v216
	v_mov_b64_e32 v[76:77], v[80:81]
	v_cndmask_b32_e32 v50, v50, v52, vcc
	v_sqrt_f32_e32 v52, v50
	v_cndmask_b32_e64 v49, v49, v51, s[42:43]
	v_mul_f32_e64 v196, v48, -v49
	v_max3_f32 v49, -v192, 0, -v196
	v_add_u32_e32 v51, -1, v52
	v_fma_f32 v53, -v51, v52, v50
	v_cmp_ge_f32_e64 s[42:43], 0, v53
	ds_bpermute_b32 v53, v235, v54
	v_add_u32_e32 v55, 1, v52
	v_cndmask_b32_e64 v51, v52, v51, s[42:43]
	v_fma_f32 v52, -v55, v52, v50
	v_cmp_lt_f32_e64 s[42:43], 0, v52
	s_waitcnt lgkmcnt(0)
	v_add_f32_e32 v52, v54, v53
	ds_bpermute_b32 v53, v236, v52
	v_cndmask_b32_e64 v51, v51, v55, s[42:43]
	v_mul_f32_e32 v54, 0x37800000, v51
	v_cndmask_b32_e32 v51, v51, v54, vcc
	v_cmp_class_f32_e32 vcc, v50, v216
	v_mov_b64_e32 v[72:73], v[80:81]
	v_mov_b64_e32 v[68:69], v[80:81]
	v_cndmask_b32_e32 v50, v51, v50, vcc
	s_waitcnt lgkmcnt(0)
	v_add_f32_e32 v51, v52, v53
	v_mul_f32_e32 v52, 0x4f800000, v51
	v_cmp_gt_f32_e32 vcc, s3, v51
	v_mul_f32_e64 v198, v48, -v50
	s_and_b32 s3, s6, 7
	v_cndmask_b32_e32 v51, v51, v52, vcc
	v_sqrt_f32_e32 v52, v51
	v_mov_b64_e32 v[64:65], v[80:81]
	v_mov_b64_e32 v[60:61], v[80:81]
	v_mov_b64_e32 v[56:57], v[80:81]
	v_add_u32_e32 v50, -1, v52
	v_fma_f32 v53, -v50, v52, v51
	v_cmp_ge_f32_e64 s[42:43], 0, v53
	v_add_u32_e32 v53, 1, v52
	v_mov_b32_e32 v193, v192
	v_cndmask_b32_e64 v50, v52, v50, s[42:43]
	v_fma_f32 v52, -v53, v52, v51
	v_cmp_lt_f32_e64 s[42:43], 0, v52
	v_mov_b32_e32 v197, v196
	v_mov_b32_e32 v199, v198
	v_cndmask_b32_e64 v50, v50, v53, s[42:43]
	v_mul_f32_e32 v52, 0x37800000, v50
	v_cndmask_b32_e32 v50, v50, v52, vcc
	v_cmp_class_f32_e32 vcc, v51, v216
	v_mov_b64_e32 v[52:53], v[80:81]
	s_mov_b32 s16, 0
	v_cndmask_b32_e32 v50, v50, v51, vcc
	v_mul_f32_e64 v200, v48, -v50
	v_max3_f32 v48, v49, -v198, -v200
	v_cmp_lt_f32_e32 vcc, s4, v48
	s_cmp_lg_u64 vcc, 0
	s_cselect_b64 s[4:5], -1, 0
	s_add_u32 s8, s44, s8
	s_addc_u32 s7, s45, s7
	s_lshl_b32 s9, s3, 8
	s_add_u32 s8, s8, s9
	s_addc_u32 s7, s7, 0
	s_add_u32 s8, s8, 0xe610080
	s_addc_u32 s9, s7, 0
	v_mov_b32_e32 v48, 0x18c000
	v_lshl_add_u64 v[204:205], s[8:9], 0, v[182:183]
	v_mad_i64_i32 v[202:203], s[6:7], s6, v48, v[188:189]
	v_lshl_add_u64 v[48:49], v[204:205], 0, v[166:167]
	global_load_dwordx4 v[112:115], v[202:203], off offset:16
	global_load_dwordx4 v[116:119], v[202:203], off
	global_load_dwordx4 v[120:123], v[202:203], off offset:32
	global_load_dwordx4 v[124:127], v[48:49], off
	v_lshl_add_u64 v[48:49], s[8:9], 0, v[184:185]
	v_lshl_add_u64 v[48:49], v[48:49], 0, v[166:167]
	global_load_dwordx4 v[128:131], v[48:49], off
	v_mov_b64_e32 v[48:49], v[80:81]
	v_mov_b32_e32 v201, v200
	s_mov_b64 s[6:7], 0
	v_mov_b64_e32 v[84:85], v[80:81]
	v_mov_b64_e32 v[88:89], v[80:81]
	v_mov_b64_e32 v[92:93], v[80:81]
	v_mov_b64_e32 v[96:97], v[80:81]
	v_mov_b64_e32 v[100:101], v[80:81]
	v_mov_b64_e32 v[104:105], v[80:81]
	v_mov_b64_e32 v[108:109], v[80:81]
	v_mov_b64_e32 v[78:79], v[82:83]
	v_mov_b64_e32 v[74:75], v[82:83]
	v_mov_b64_e32 v[70:71], v[82:83]
	v_mov_b64_e32 v[66:67], v[82:83]
	v_mov_b64_e32 v[62:63], v[82:83]
	v_mov_b64_e32 v[58:59], v[82:83]
	v_mov_b64_e32 v[54:55], v[82:83]
	v_mov_b64_e32 v[50:51], v[82:83]
	v_mov_b64_e32 v[194:195], v[190:191]
	s_waitcnt vmcnt(3)
	ds_write_b128 v237, v[116:119]
	ds_write_b128 v237, v[112:115] offset:16
	s_waitcnt vmcnt(2)
	ds_write_b128 v237, v[120:123] offset:32
	s_waitcnt vmcnt(1)
	ds_write_b128 v238, v[124:127] offset:53248
	s_waitcnt vmcnt(0)
	ds_write_b128 v238, v[128:131] offset:63488
	s_waitcnt lgkmcnt(0)
	s_barrier

; __device__ __forceinline__ uint32_t pack2(float a, float b) { uint32_t r; asm("v_cvt_pk_bf16_f32 %0, %1, %2" : "=v"(r) : "v"(a), "v"(b)); return r; }
; #define MFMA16(a, b, c) __builtin_amdgcn_mfma_f32_16x16x32_bf16(a, b, c, 0, 0, 0)
; __device__ __forceinline__ void attn_phase(const Params& p, char* smem) {
;     ...
;       if (active) {
;         const bf16_t* cK = Ks + buf * KT * KLD;
;         const bf16_t* cV = Vt + buf * 64 * VLD;
; #pragma unroll 1
;         for (int ks = 0; ks < 4; ++ks) {
;           uint32_t pfu[4][4];
; #pragma unroll
;           for (int kf = 0; kf < 2; ++kf) {
;             f32x4 sT[4];
; #pragma unroll
;             for (int g = 0; g < 4; ++g) sT[g] = (f32x4){0.f, 0.f, 0.f, 0.f};
; #pragma unroll
;             for (int ds = 0; ds < 3; ++ds) {
;               bf16x8 ka = *(const bf16x8*)(cK + (ks * 32 + kf * 16 + fr) * KLD + ds * 32 + fq * 8);
; #pragma unroll
;               for (int g = 0; g < 4; ++g) sT[g] = MFMA16(ka, qf[g][ds], sT[g]);
;             }
;             if (stab) {
; #pragma unroll
;               for (int g = 0; g < 4; ++g) { sT[g][0] += mneg[g]; sT[g][1] += mneg[g]; sT[g][2] += mneg[g]; sT[g][3] += mneg[g]; }
;             }
; #pragma unroll
;             for (int g = 0; g < 4; ++g) {
;               float p0 = __builtin_amdgcn_exp2f(sT[g][0]), p1 = __builtin_amdgcn_exp2f(sT[g][1]);
;               float p2 = __builtin_amdgcn_exp2f(sT[g][2]), p3 = __builtin_amdgcn_exp2f(sT[g][3]);
;               { float l_ = lrun[g]; l_ += p0; l_ += p1; l_ += p2; l_ += p3; lrun[g] = l_; }
;               pfu[g][kf * 2] = pack2(p0, p1); pfu[g][kf * 2 + 1] = pack2(p2, p3);
;             }
;           }
;           bf16x8 pf[4];
; #pragma unroll
;           for (int g = 0; g < 4; ++g) {
;             union { uint32_t u[4]; bf16x8 v; } cvt;
;             cvt.u[0] = pfu[g][0]; cvt.u[1] = pfu[g][1]; cvt.u[2] = pfu[g][2]; cvt.u[3] = pfu[g][3];
;             pf[g] = cvt.v;
;           }
; #pragma unroll
;           for (int dvf = 0; dvf < 4; ++dvf) {
;             const bf16_t* vp = cV + (dvf * 16 + fr) * VLD + ks * 32 + fq * 4;
;             union { uint2 u[2]; bf16x8 v; } va;
;             va.u[0] = *(const uint2*)(vp);
;             va.u[1] = *(const uint2*)(vp + 16);
; #pragma unroll
;             for (int g = 0; g < 4; ++g) oT[g][dvf] = MFMA16(va.v, pf[g], oT[g][dvf]);
;           }
;         }
.LBB0_413:
	s_and_saveexec_b64 s[10:11], s[40:41]
	s_cbranch_execz .LBB0_420
	v_cndmask_b32_e64 v132, 0, 1, s[6:7]
	s_movk_i32 s17, 0x5000
	v_mul_lo_u32 v133, v132, s17
	s_movk_i32 s17, 0x6800
	v_mul_lo_u32 v132, v132, s17
	v_add_u32_e32 v242, v240, v133
	v_add_u32_e32 v243, v241, v132
	s_mov_b32 s17, 4
	s_and_b64 vcc, exec, s[4:5]
	s_cbranch_vccnz .LBB0_416
	v_add_u32_e32 v206, 0xd000, v242
	ds_read_b128 v[132:135], v243
	ds_read_b128 v[136:139], v243 offset:64
	ds_read_b128 v[140:143], v243 offset:128
	s_mov_b32 s17, 3
.Lattn_fast_loop:
	ds_read_b128 v[148:151], v243 offset:3328
	ds_read_b128 v[152:155], v243 offset:3392
	ds_read_b128 v[156:159], v243 offset:3456
	s_waitcnt lgkmcnt(5)
	v_mfma_f32_16x16x32_bf16 v[244:247], v[132:135], v[0:3], 0
	v_mfma_f32_16x16x32_bf16 v[248:251], v[132:135], v[12:15], 0
	v_mfma_f32_16x16x32_bf16 v[208:211], v[132:135], v[24:27], 0
	v_mfma_f32_16x16x32_bf16 v[212:215], v[132:135], v[36:39], 0
	s_waitcnt lgkmcnt(4)
	v_mfma_f32_16x16x32_bf16 v[244:247], v[136:139], v[4:7], v[244:247]
	v_mfma_f32_16x16x32_bf16 v[248:251], v[136:139], v[16:19], v[248:251]
	v_mfma_f32_16x16x32_bf16 v[208:211], v[136:139], v[28:31], v[208:211]
	v_mfma_f32_16x16x32_bf16 v[212:215], v[136:139], v[40:43], v[212:215]
	s_waitcnt lgkmcnt(3)
	v_mfma_f32_16x16x32_bf16 v[244:247], v[140:143], v[8:11], v[244:247]
	v_mfma_f32_16x16x32_bf16 v[248:251], v[140:143], v[20:23], v[248:251]
	v_mfma_f32_16x16x32_bf16 v[208:211], v[140:143], v[32:35], v[208:211]
	v_mfma_f32_16x16x32_bf16 v[212:215], v[140:143], v[44:47], v[212:215]
	s_waitcnt lgkmcnt(2)
	v_mfma_f32_16x16x32_bf16 v[132:135], v[148:151], v[0:3], 0
	v_mfma_f32_16x16x32_bf16 v[136:139], v[148:151], v[12:15], 0
	v_mfma_f32_16x16x32_bf16 v[140:143], v[148:151], v[24:27], 0
	v_mfma_f32_16x16x32_bf16 v[144:147], v[148:151], v[36:39], 0
	s_waitcnt lgkmcnt(1)
	v_exp_f32_e32 v244, v244
	v_exp_f32_e32 v245, v245
	v_exp_f32_e32 v246, v246
	v_exp_f32_e32 v247, v247
	v_exp_f32_e32 v248, v248
	v_mfma_f32_16x16x32_bf16 v[132:135], v[152:155], v[4:7], v[132:135]
	v_exp_f32_e32 v249, v249
	v_exp_f32_e32 v250, v250
	v_exp_f32_e32 v251, v251
	v_add_f32_e32 v195, v195, v244
	v_add_f32_e32 v195, v195, v245
	v_mfma_f32_16x16x32_bf16 v[136:139], v[152:155], v[16:19], v[136:139]
	v_add_f32_e32 v195, v195, v246
	v_add_f32_e32 v195, v195, v247
	v_cvt_pk_bf16_f32 v244, v244, v245
	v_cvt_pk_bf16_f32 v245, v246, v247
	v_add_f32_e32 v194, v194, v248
	v_mfma_f32_16x16x32_bf16 v[140:143], v[152:155], v[28:31], v[140:143]
	v_add_f32_e32 v194, v194, v249
	v_add_f32_e32 v194, v194, v250
	v_add_f32_e32 v194, v194, v251
	v_cvt_pk_bf16_f32 v248, v248, v249
	v_cvt_pk_bf16_f32 v249, v250, v251
	v_mfma_f32_16x16x32_bf16 v[144:147], v[152:155], v[40:43], v[144:147]
	ds_read_b64_tr_b16 v[160:161], v206 offset:96
	ds_read_b64_tr_b16 v[162:163], v206 offset:2656
	ds_read_b64_tr_b16 v[148:149], v206 offset:0
	ds_read_b64_tr_b16 v[150:151], v206 offset:2560
	ds_read_b64_tr_b16 v[152:153], v206 offset:32
	ds_read_b64_tr_b16 v[154:155], v206 offset:2592
	s_waitcnt lgkmcnt(6)
	v_exp_f32_e32 v208, v208
	v_exp_f32_e32 v209, v209
	v_exp_f32_e32 v210, v210
	v_exp_f32_e32 v211, v211
	v_exp_f32_e32 v212, v212
	v_mfma_f32_16x16x32_bf16 v[132:135], v[156:159], v[8:11], v[132:135]
	v_exp_f32_e32 v213, v213
	v_exp_f32_e32 v214, v214
	v_exp_f32_e32 v215, v215
	v_add_f32_e32 v191, v191, v208
	v_add_f32_e32 v191, v191, v209
	v_mfma_f32_16x16x32_bf16 v[136:139], v[156:159], v[20:23], v[136:139]
	v_add_f32_e32 v191, v191, v210
	v_add_f32_e32 v191, v191, v211
	v_cvt_pk_bf16_f32 v208, v208, v209
	v_cvt_pk_bf16_f32 v209, v210, v211
	v_add_f32_e32 v190, v190, v212
	v_mfma_f32_16x16x32_bf16 v[140:143], v[156:159], v[32:35], v[140:143]
	v_add_f32_e32 v190, v190, v213
	v_add_f32_e32 v190, v190, v214
	v_add_f32_e32 v190, v190, v215
	v_cvt_pk_bf16_f32 v212, v212, v213
	v_cvt_pk_bf16_f32 v213, v214, v215
	v_mfma_f32_16x16x32_bf16 v[144:147], v[156:159], v[44:47], v[144:147]
	ds_read_b64_tr_b16 v[156:157], v206 offset:64
	ds_read_b64_tr_b16 v[158:159], v206 offset:2624
	v_add_u32_e32 v243, 0x1a00, v243
	v_exp_f32_e32 v132, v132
	v_exp_f32_e32 v133, v133
	v_exp_f32_e32 v134, v134
	v_exp_f32_e32 v135, v135
	v_add_f32_e32 v195, v195, v132
	v_add_f32_e32 v195, v195, v133
	v_add_f32_e32 v195, v195, v134
	v_add_f32_e32 v195, v195, v135
	v_cvt_pk_bf16_f32 v246, v132, v133
	v_cvt_pk_bf16_f32 v247, v134, v135
	ds_read_b128 v[132:135], v243
	s_waitcnt lgkmcnt(1)
	v_mfma_f32_16x16x32_bf16 v[108:111], v[148:151], v[244:247], v[108:111]
	v_exp_f32_e32 v136, v136
	v_exp_f32_e32 v137, v137
	v_exp_f32_e32 v138, v138
	v_mfma_f32_16x16x32_bf16 v[104:107], v[152:155], v[244:247], v[104:107]
	v_exp_f32_e32 v139, v139
	v_add_f32_e32 v194, v194, v136
	v_add_f32_e32 v194, v194, v137
	v_mfma_f32_16x16x32_bf16 v[100:103], v[156:159], v[244:247], v[100:103]
	v_add_f32_e32 v194, v194, v138
	v_add_f32_e32 v194, v194, v139
	v_cvt_pk_bf16_f32 v250, v136, v137
	v_cvt_pk_bf16_f32 v251, v138, v139
	v_mfma_f32_16x16x32_bf16 v[96:99], v[160:163], v[244:247], v[96:99]
	ds_read_b128 v[136:139], v243 offset:64
	v_mfma_f32_16x16x32_bf16 v[92:95], v[148:151], v[248:251], v[92:95]
	v_exp_f32_e32 v140, v140
	v_exp_f32_e32 v141, v141
	v_exp_f32_e32 v142, v142
	v_mfma_f32_16x16x32_bf16 v[88:91], v[152:155], v[248:251], v[88:91]
	v_exp_f32_e32 v143, v143
	v_add_f32_e32 v191, v191, v140
	v_add_f32_e32 v191, v191, v141
	v_mfma_f32_16x16x32_bf16 v[84:87], v[156:159], v[248:251], v[84:87]
	v_add_f32_e32 v191, v191, v142
	v_add_f32_e32 v191, v191, v143
	v_cvt_pk_bf16_f32 v210, v140, v141
	v_cvt_pk_bf16_f32 v211, v142, v143
	v_mfma_f32_16x16x32_bf16 v[80:83], v[160:163], v[248:251], v[80:83]
	ds_read_b128 v[140:143], v243 offset:128
	v_mfma_f32_16x16x32_bf16 v[76:79], v[148:151], v[208:211], v[76:79]
	v_exp_f32_e32 v144, v144
	v_exp_f32_e32 v145, v145
	v_exp_f32_e32 v146, v146
	v_mfma_f32_16x16x32_bf16 v[72:75], v[152:155], v[208:211], v[72:75]
	v_exp_f32_e32 v147, v147
	v_add_f32_e32 v190, v190, v144
	v_add_f32_e32 v190, v190, v145
	v_mfma_f32_16x16x32_bf16 v[68:71], v[156:159], v[208:211], v[68:71]
	v_add_f32_e32 v190, v190, v146
	v_add_f32_e32 v190, v190, v147
	v_cvt_pk_bf16_f32 v214, v144, v145
	v_cvt_pk_bf16_f32 v215, v146, v147
	v_mfma_f32_16x16x32_bf16 v[64:67], v[160:163], v[208:211], v[64:67]
	v_add_u32_e32 v206, 0x1400, v206
	v_mfma_f32_16x16x32_bf16 v[60:63], v[148:151], v[212:215], v[60:63]
	v_mfma_f32_16x16x32_bf16 v[56:59], v[152:155], v[212:215], v[56:59]
	v_mfma_f32_16x16x32_bf16 v[52:55], v[156:159], v[212:215], v[52:55]
	v_mfma_f32_16x16x32_bf16 v[48:51], v[160:163], v[212:215], v[48:51]
	s_add_i32 s17, s17, -1
	s_cmp_lg_u32 s17, 0
	s_cbranch_scc1 .Lattn_fast_loop
; __device__ __forceinline__ uint32_t pack2(float a, float b) { uint32_t r; asm("v_cvt_pk_bf16_f32 %0, %1, %2" : "=v"(r) : "v"(a), "v"(b)); return r; }
; #define MFMA16(a, b, c) __builtin_amdgcn_mfma_f32_16x16x32_bf16(a, b, c, 0, 0, 0)
; __device__ __forceinline__ void attn_phase(const Params& p, char* smem) {
;     ...
;       if (active) {
;         const bf16_t* cK = Ks + buf * KT * KLD;
;         const bf16_t* cV = Vt + buf * 64 * VLD;
; #pragma unroll 1
;         for (int ks = 0; ks < 4; ++ks) {
;           uint32_t pfu[4][4];
; #pragma unroll
;           for (int kf = 0; kf < 2; ++kf) {
;             f32x4 sT[4];
; #pragma unroll
;             for (int g = 0; g < 4; ++g) sT[g] = (f32x4){0.f, 0.f, 0.f, 0.f};
; #pragma unroll
;             for (int ds = 0; ds < 3; ++ds) {
;               bf16x8 ka = *(const bf16x8*)(cK + (ks * 32 + kf * 16 + fr) * KLD + ds * 32 + fq * 8);
; #pragma unroll
;               for (int g = 0; g < 4; ++g) sT[g] = MFMA16(ka, qf[g][ds], sT[g]);
;             }
;             if (stab) {
; #pragma unroll
;               for (int g = 0; g < 4; ++g) { sT[g][0] += mneg[g]; sT[g][1] += mneg[g]; sT[g][2] += mneg[g]; sT[g][3] += mneg[g]; }
;             }
; #pragma unroll
;             for (int g = 0; g < 4; ++g) {
;               float p0 = __builtin_amdgcn_exp2f(sT[g][0]), p1 = __builtin_amdgcn_exp2f(sT[g][1]);
;               float p2 = __builtin_amdgcn_exp2f(sT[g][2]), p3 = __builtin_amdgcn_exp2f(sT[g][3]);
;               { float l_ = lrun[g]; l_ += p0; l_ += p1; l_ += p2; l_ += p3; lrun[g] = l_; }
;               pfu[g][kf * 2] = pack2(p0, p1); pfu[g][kf * 2 + 1] = pack2(p2, p3);
;             }
;           }
;           bf16x8 pf[4];
; #pragma unroll
;           for (int g = 0; g < 4; ++g) {
;             union { uint32_t u[4]; bf16x8 v; } cvt;
;             cvt.u[0] = pfu[g][0]; cvt.u[1] = pfu[g][1]; cvt.u[2] = pfu[g][2]; cvt.u[3] = pfu[g][3];
;             pf[g] = cvt.v;
;           }
; #pragma unroll
;           for (int dvf = 0; dvf < 4; ++dvf) {
;             const bf16_t* vp = cV + (dvf * 16 + fr) * VLD + ks * 32 + fq * 4;
;             union { uint2 u[2]; bf16x8 v; } va;
;             va.u[0] = *(const uint2*)(vp);
;             va.u[1] = *(const uint2*)(vp + 16);
; #pragma unroll
;             for (int g = 0; g < 4; ++g) oT[g][dvf] = MFMA16(va.v, pf[g], oT[g][dvf]);
;           }
;         }
	ds_read_b128 v[148:151], v243 offset:3328
	ds_read_b128 v[152:155], v243 offset:3392
	ds_read_b128 v[156:159], v243 offset:3456
	s_waitcnt lgkmcnt(5)
	v_mfma_f32_16x16x32_bf16 v[244:247], v[132:135], v[0:3], 0
	v_mfma_f32_16x16x32_bf16 v[248:251], v[132:135], v[12:15], 0
	v_mfma_f32_16x16x32_bf16 v[208:211], v[132:135], v[24:27], 0
	v_mfma_f32_16x16x32_bf16 v[212:215], v[132:135], v[36:39], 0
	s_waitcnt lgkmcnt(4)
	v_mfma_f32_16x16x32_bf16 v[244:247], v[136:139], v[4:7], v[244:247]
	v_mfma_f32_16x16x32_bf16 v[248:251], v[136:139], v[16:19], v[248:251]
	v_mfma_f32_16x16x32_bf16 v[208:211], v[136:139], v[28:31], v[208:211]
	v_mfma_f32_16x16x32_bf16 v[212:215], v[136:139], v[40:43], v[212:215]
	s_waitcnt lgkmcnt(3)
	v_mfma_f32_16x16x32_bf16 v[244:247], v[140:143], v[8:11], v[244:247]
	v_mfma_f32_16x16x32_bf16 v[248:251], v[140:143], v[20:23], v[248:251]
	v_mfma_f32_16x16x32_bf16 v[208:211], v[140:143], v[32:35], v[208:211]
	v_mfma_f32_16x16x32_bf16 v[212:215], v[140:143], v[44:47], v[212:215]
	s_waitcnt lgkmcnt(2)
	v_mfma_f32_16x16x32_bf16 v[132:135], v[148:151], v[0:3], 0
	v_mfma_f32_16x16x32_bf16 v[136:139], v[148:151], v[12:15], 0
	v_mfma_f32_16x16x32_bf16 v[140:143], v[148:151], v[24:27], 0
	v_mfma_f32_16x16x32_bf16 v[144:147], v[148:151], v[36:39], 0
	s_waitcnt lgkmcnt(1)
	v_exp_f32_e32 v244, v244
	v_exp_f32_e32 v245, v245
	v_exp_f32_e32 v246, v246
	v_exp_f32_e32 v247, v247
	v_exp_f32_e32 v248, v248
	v_mfma_f32_16x16x32_bf16 v[132:135], v[152:155], v[4:7], v[132:135]
	v_exp_f32_e32 v249, v249
	v_exp_f32_e32 v250, v250
	v_exp_f32_e32 v251, v251
	v_add_f32_e32 v195, v195, v244
	v_add_f32_e32 v195, v195, v245
	v_mfma_f32_16x16x32_bf16 v[136:139], v[152:155], v[16:19], v[136:139]
	v_add_f32_e32 v195, v195, v246
	v_add_f32_e32 v195, v195, v247
	v_cvt_pk_bf16_f32 v244, v244, v245
	v_cvt_pk_bf16_f32 v245, v246, v247
	v_add_f32_e32 v194, v194, v248
	v_mfma_f32_16x16x32_bf16 v[140:143], v[152:155], v[28:31], v[140:143]
	v_add_f32_e32 v194, v194, v249
	v_add_f32_e32 v194, v194, v250
	v_add_f32_e32 v194, v194, v251
	v_cvt_pk_bf16_f32 v248, v248, v249
	v_cvt_pk_bf16_f32 v249, v250, v251
	v_mfma_f32_16x16x32_bf16 v[144:147], v[152:155], v[40:43], v[144:147]
	ds_read_b64_tr_b16 v[160:161], v206 offset:96
	ds_read_b64_tr_b16 v[162:163], v206 offset:2656
	ds_read_b64_tr_b16 v[148:149], v206 offset:0
	ds_read_b64_tr_b16 v[150:151], v206 offset:2560
	ds_read_b64_tr_b16 v[152:153], v206 offset:32
	ds_read_b64_tr_b16 v[154:155], v206 offset:2592
	s_waitcnt lgkmcnt(6)
	v_exp_f32_e32 v208, v208
	v_exp_f32_e32 v209, v209
	v_exp_f32_e32 v210, v210
	v_exp_f32_e32 v211, v211
	v_exp_f32_e32 v212, v212
	v_mfma_f32_16x16x32_bf16 v[132:135], v[156:159], v[8:11], v[132:135]
	v_exp_f32_e32 v213, v213
	v_exp_f32_e32 v214, v214
	v_exp_f32_e32 v215, v215
	v_add_f32_e32 v191, v191, v208
	v_add_f32_e32 v191, v191, v209
	v_mfma_f32_16x16x32_bf16 v[136:139], v[156:159], v[20:23], v[136:139]
	v_add_f32_e32 v191, v191, v210
	v_add_f32_e32 v191, v191, v211
	v_cvt_pk_bf16_f32 v208, v208, v209
	v_cvt_pk_bf16_f32 v209, v210, v211
	v_add_f32_e32 v190, v190, v212
	v_mfma_f32_16x16x32_bf16 v[140:143], v[156:159], v[32:35], v[140:143]
	v_add_f32_e32 v190, v190, v213
	v_add_f32_e32 v190, v190, v214
	v_add_f32_e32 v190, v190, v215
	v_cvt_pk_bf16_f32 v212, v212, v213
	v_cvt_pk_bf16_f32 v213, v214, v215
	v_mfma_f32_16x16x32_bf16 v[144:147], v[156:159], v[44:47], v[144:147]
	ds_read_b64_tr_b16 v[156:157], v206 offset:64
	ds_read_b64_tr_b16 v[158:159], v206 offset:2624
	v_exp_f32_e32 v132, v132
	v_exp_f32_e32 v133, v133
	v_exp_f32_e32 v134, v134
	v_exp_f32_e32 v135, v135
	v_add_f32_e32 v195, v195, v132
	v_add_f32_e32 v195, v195, v133
	v_add_f32_e32 v195, v195, v134
	v_add_f32_e32 v195, v195, v135
	v_cvt_pk_bf16_f32 v246, v132, v133
	v_cvt_pk_bf16_f32 v247, v134, v135
	s_waitcnt lgkmcnt(0)
	s_nop 0
	v_mfma_f32_16x16x32_bf16 v[108:111], v[148:151], v[244:247], v[108:111]
	v_exp_f32_e32 v136, v136
	v_exp_f32_e32 v137, v137
	v_exp_f32_e32 v138, v138
	v_mfma_f32_16x16x32_bf16 v[104:107], v[152:155], v[244:247], v[104:107]
	v_exp_f32_e32 v139, v139
	v_add_f32_e32 v194, v194, v136
	v_add_f32_e32 v194, v194, v137
	v_mfma_f32_16x16x32_bf16 v[100:103], v[156:159], v[244:247], v[100:103]
	v_add_f32_e32 v194, v194, v138
	v_add_f32_e32 v194, v194, v139
	v_cvt_pk_bf16_f32 v250, v136, v137
	v_cvt_pk_bf16_f32 v251, v138, v139
	v_mfma_f32_16x16x32_bf16 v[96:99], v[160:163], v[244:247], v[96:99]
	s_nop 0
	v_mfma_f32_16x16x32_bf16 v[92:95], v[148:151], v[248:251], v[92:95]
	v_exp_f32_e32 v140, v140
	v_exp_f32_e32 v141, v141
	v_exp_f32_e32 v142, v142
	v_mfma_f32_16x16x32_bf16 v[88:91], v[152:155], v[248:251], v[88:91]
	v_exp_f32_e32 v143, v143
	v_add_f32_e32 v191, v191, v140
	v_add_f32_e32 v191, v191, v141
	v_mfma_f32_16x16x32_bf16 v[84:87], v[156:159], v[248:251], v[84:87]
	v_add_f32_e32 v191, v191, v142
	v_add_f32_e32 v191, v191, v143
	v_cvt_pk_bf16_f32 v210, v140, v141
	v_cvt_pk_bf16_f32 v211, v142, v143
	v_mfma_f32_16x16x32_bf16 v[80:83], v[160:163], v[248:251], v[80:83]
	s_nop 0
	v_mfma_f32_16x16x32_bf16 v[76:79], v[148:151], v[208:211], v[76:79]
	v_exp_f32_e32 v144, v144
	v_exp_f32_e32 v145, v145
	v_exp_f32_e32 v146, v146
	v_mfma_f32_16x16x32_bf16 v[72:75], v[152:155], v[208:211], v[72:75]
	v_exp_f32_e32 v147, v147
	v_add_f32_e32 v190, v190, v144
	v_add_f32_e32 v190, v190, v145
	v_mfma_f32_16x16x32_bf16 v[68:71], v[156:159], v[208:211], v[68:71]
	v_add_f32_e32 v190, v190, v146
	v_add_f32_e32 v190, v190, v147
	v_cvt_pk_bf16_f32 v214, v144, v145
	v_cvt_pk_bf16_f32 v215, v146, v147
	v_mfma_f32_16x16x32_bf16 v[64:67], v[160:163], v[208:211], v[64:67]
	s_nop 0
	v_mfma_f32_16x16x32_bf16 v[60:63], v[148:151], v[212:215], v[60:63]
	v_mfma_f32_16x16x32_bf16 v[56:59], v[152:155], v[212:215], v[56:59]
	v_mfma_f32_16x16x32_bf16 v[52:55], v[156:159], v[212:215], v[52:55]
	v_mfma_f32_16x16x32_bf16 v[48:51], v[160:163], v[212:215], v[48:51]
	s_branch .LBB0_420
; __device__ __forceinline__ uint32_t pack2(float a, float b) { uint32_t r; asm("v_cvt_pk_bf16_f32 %0, %1, %2" : "=v"(r) : "v"(a), "v"(b)); return r; }
; #define MFMA16(a, b, c) __builtin_amdgcn_mfma_f32_16x16x32_bf16(a, b, c, 0, 0, 0)
; __device__ __forceinline__ void attn_phase(const Params& p, char* smem) {
;     ...
;             if (stab) {
; #pragma unroll
;               for (int g = 0; g < 4; ++g) { sT[g][0] += mneg[g]; sT[g][1] += mneg[g]; sT[g][2] += mneg[g]; sT[g][3] += mneg[g]; }
;             }
; #pragma unroll
;             for (int g = 0; g < 4; ++g) {
;               float p0 = __builtin_amdgcn_exp2f(sT[g][0]), p1 = __builtin_amdgcn_exp2f(sT[g][1]);
;               float p2 = __builtin_amdgcn_exp2f(sT[g][2]), p3 = __builtin_amdgcn_exp2f(sT[g][3]);
;               { float l_ = lrun[g]; l_ += p0; l_ += p1; l_ += p2; l_ += p3; lrun[g] = l_; }
;               pfu[g][kf * 2] = pack2(p0, p1); pfu[g][kf * 2 + 1] = pack2(p2, p3);
;             }
;           }
;           bf16x8 pf[4];
; #pragma unroll
;           for (int g = 0; g < 4; ++g) {
;             union { uint32_t u[4]; bf16x8 v; } cvt;
;             cvt.u[0] = pfu[g][0]; cvt.u[1] = pfu[g][1]; cvt.u[2] = pfu[g][2]; cvt.u[3] = pfu[g][3];
;             pf[g] = cvt.v;
;           }
; #pragma unroll
;           for (int dvf = 0; dvf < 4; ++dvf) {
;             const bf16_t* vp = cV + (dvf * 16 + fr) * VLD + ks * 32 + fq * 4;
;             union { uint2 u[2]; bf16x8 v; } va;
;             va.u[0] = *(const uint2*)(vp);
;             va.u[1] = *(const uint2*)(vp + 16);
; #pragma unroll
;             for (int g = 0; g < 4; ++g) oT[g][dvf] = MFMA16(va.v, pf[g], oT[g][dvf]);
;           }
;         }
.LBB0_415:
	v_pk_add_f32 v[142:143], v[190:191], v[142:143]
	v_pk_add_f32 v[134:135], v[194:195], v[208:209]
	v_pk_add_f32 v[142:143], v[214:215], v[142:143]
	v_pk_add_f32 v[134:135], v[206:207], v[134:135]
	v_pk_add_f32 v[142:143], v[212:213], v[142:143]
	v_exp_f32_e32 v161, v161
	v_pk_add_f32 v[138:139], v[138:139], v[142:143]
	v_exp_f32_e32 v143, v160
	v_exp_f32_e32 v142, v156
	v_exp_f32_e32 v160, v157
	v_pk_add_f32 v[134:135], v[210:211], v[134:135]
	v_exp_f32_e32 v173, v162
	v_exp_f32_e32 v172, v158
	v_pk_add_f32 v[134:135], v[146:147], v[134:135]
	v_exp_f32_e32 v163, v163
	v_exp_f32_e32 v162, v159
	v_pk_add_f32 v[134:135], v[134:135], v[142:143]
	v_exp_f32_e32 v149, v149
	v_pk_add_f32 v[134:135], v[160:161], v[134:135]
	v_exp_f32_e32 v157, v150
	v_pk_add_f32 v[134:135], v[172:173], v[134:135]
	v_exp_f32_e32 v156, v154
	v_pk_add_f32 v[194:195], v[162:163], v[134:135]
	v_exp_f32_e32 v135, v148
	v_exp_f32_e32 v134, v152
	v_exp_f32_e32 v148, v153
	v_exp_f32_e32 v151, v151
	v_exp_f32_e32 v150, v155
	v_pk_add_f32 v[138:139], v[138:139], v[134:135]
	v_cvt_pk_bf16_f32 v134, v134, v148
	v_cvt_pk_bf16_f32 v146, v143, v161
	v_cvt_pk_bf16_f32 v147, v173, v163
	v_cvt_pk_bf16_f32 v142, v142, v160
	v_cvt_pk_bf16_f32 v143, v172, v162
	s_nop 0
	v_pk_add_f32 v[138:139], v[148:149], v[138:139]
	s_add_i32 s17, s17, -1
	v_pk_add_f32 v[152:153], v[156:157], v[138:139]
	v_cvt_pk_bf16_f32 v138, v135, v149
	v_cvt_pk_bf16_f32 v139, v157, v151
	v_cvt_pk_bf16_f32 v135, v156, v150
	v_add_u32_e32 v243, 0x1a00, v243
	v_pk_add_f32 v[190:191], v[150:151], v[152:153]
	v_add_u32_e32 v152, 0, v242
	v_add_u32_e32 v206, 0xd000, v152
	ds_read_b64_tr_b16 v[148:149], v206
	ds_read_b64_tr_b16 v[150:151], v206 offset:2560
	v_add_u32_e32 v242, 0x1400, v242
	s_waitcnt lgkmcnt(0)
	v_mfma_f32_16x16x32_bf16 v[108:111], v[148:151], v[144:147], v[108:111]
	s_cmp_lg_u32 s17, 0
	v_mfma_f32_16x16x32_bf16 v[92:95], v[148:151], v[140:143], v[92:95]
	v_mfma_f32_16x16x32_bf16 v[76:79], v[148:151], v[136:139], v[76:79]
	v_mfma_f32_16x16x32_bf16 v[60:63], v[148:151], v[132:135], v[60:63]
	ds_read_b64_tr_b16 v[148:149], v206 offset:32
	ds_read_b64_tr_b16 v[150:151], v206 offset:2592
	s_waitcnt lgkmcnt(0)
	v_mfma_f32_16x16x32_bf16 v[104:107], v[148:151], v[144:147], v[104:107]
	v_mfma_f32_16x16x32_bf16 v[88:91], v[148:151], v[140:143], v[88:91]
	v_mfma_f32_16x16x32_bf16 v[72:75], v[148:151], v[136:139], v[72:75]
	v_mfma_f32_16x16x32_bf16 v[56:59], v[148:151], v[132:135], v[56:59]
	ds_read_b64_tr_b16 v[148:149], v206 offset:64
	ds_read_b64_tr_b16 v[150:151], v206 offset:2624
	s_waitcnt lgkmcnt(0)
	v_mfma_f32_16x16x32_bf16 v[100:103], v[148:151], v[144:147], v[100:103]
	v_mfma_f32_16x16x32_bf16 v[84:87], v[148:151], v[140:143], v[84:87]
	v_mfma_f32_16x16x32_bf16 v[68:71], v[148:151], v[136:139], v[68:71]
	v_mfma_f32_16x16x32_bf16 v[52:55], v[148:151], v[132:135], v[52:55]
	ds_read_b64_tr_b16 v[148:149], v206 offset:96
	ds_read_b64_tr_b16 v[150:151], v206 offset:2656
	s_waitcnt lgkmcnt(0)
	v_mfma_f32_16x16x32_bf16 v[96:99], v[148:151], v[144:147], v[96:99]
	v_mfma_f32_16x16x32_bf16 v[80:83], v[148:151], v[140:143], v[80:83]
	v_mfma_f32_16x16x32_bf16 v[64:67], v[148:151], v[136:139], v[64:67]
	v_mfma_f32_16x16x32_bf16 v[48:51], v[148:151], v[132:135], v[48:51]
	s_cbranch_scc0 .LBB0_420

; __device__ __forceinline__ void attn_phase(const Params& p, char* smem) {
;     ...
;       if (kt + 1 < nkt) {
;         bf16_t* dK = Ks + (buf ^ 1) * KT * KLD;
;         bf16_t* dV = Vt + (buf ^ 1) * 64 * VLD;
;         *(uint4*)(dK + klo) = rk0; *(uint4*)(dK + klo + 8) = rk1; *(uint4*)(dK + klo + 16) = rk2;
;         vt_scatter(dV + (vch * 8) * VLD + vkey0, VLD, rv0); vt_scatter(dV + (vch * 8) * VLD + vkey0 + 64, VLD, rv1);
;       }
.LBB0_420:
	s_or_b64 exec, exec, s[10:11]
	s_andn2_b64 vcc, exec, s[8:9]
	s_cbranch_vccnz .LBB0_422
	s_andn2_b32 s8, 1, s16
	s_mul_i32 s9, s8, 0x6800
	s_mulk_i32 s8, 0x5000
	v_add_u32_e32 v132, s9, v237
	s_waitcnt vmcnt(3)
	ds_write_b128 v132, v[116:119]
	ds_write_b128 v132, v[112:115] offset:16
	s_waitcnt vmcnt(2)
	ds_write_b128 v132, v[120:123] offset:32
	v_add_u32_e32 v132, s8, v238
	s_waitcnt vmcnt(1)
	ds_write_b128 v132, v[124:127] offset:53248
	s_waitcnt vmcnt(0)
	ds_write_b128 v132, v[128:131] offset:63488
